# single-chain RWKV scan + the 704 FFN2-down conversion tiles moved from the retention workgroups' P7 tail to P11's idle last-round workgroups (172-255)
# speedup vs baseline: 1.0046x; 1.0046x over previous
; __device__ __forceinline__ void tconv_list(const float* wg, const float* wu, const float* wd, const float* win, const float* wout, unsigned char* ws, const int ntiles, LAS float* t, const int wv) {
;     ...
;     for (; i < ntiles; i += G) {
;         const TDesc d = tconv_desc(wg, wu, wd, win, wout, ws, i);
;         { const TDesc dn = tconv_desc(wg, wu, wd, win, wout, ws, i + G < ntiles ? i + G : i);
; #pragma unroll
;             for (int e = 0; e < 8; ++e) { const int idx = e * 512 + tid, r = idx >> 6, c = idx & 63; nxt[e] = __builtin_nontemporal_load(dn.W + (size_t)(dn.k0 + r) * dn.N + dn.n0 + c); } }
.Ltc2_loop:
	s_add_u32 s4, s4, 128
	s_cmp_lt_u32 s4, 1408
	s_cselect_b32 s31, 1, 0
	s_cbranch_scc0 .Ltc2_nonexta
	v_writelane_b32 v40, s8, 32
	v_writelane_b32 v40, s9, 33
	s_cmp_lt_u32 s4, 704
	s_cbranch_scc0 .Ltc2_seg1_1
	s_mov_b32 s7, s4
	s_and_b32 s8, s7, 15
	s_lshr_b32 s9, s7, 4
	s_mul_i32 s7, s8, 720896
	s_lshl_b32 s29, s9, 8
	s_add_u32 s7, s7, s29
	s_mul_i32 s29, s28, 11264
	s_add_u32 s7, s7, s29
	s_add_u32 s10, s18, s7
	s_addc_u32 s11, s19, 0
	s_lshr_b32 s7, s9, 1
	s_lshl_b32 s7, s7, 8
	s_and_b32 s29, s9, 1
	s_lshl_b32 s29, s29, 6
	s_add_u32 s7, s7, s29
	s_mul_i32 s7, s7, 2048
	s_lshl_b32 s29, s8, 7
	s_add_u32 s7, s7, s29
	s_mul_i32 s29, s28, 4096
	s_add_u32 s7, s7, s29
	s_add_u32 s12, s26, 0x2100000
	s_addc_u32 s13, s27, 0
	s_add_u32 s12, s12, s7
	s_addc_u32 s13, s13, 0
	s_mov_b32 s14, 90112
	s_mov_b32 s15, 32768
	s_movk_i32 s16, 2048
	s_branch .Ltc2_segend_1

; __device__ __forceinline__ unsigned cvt_pk_bf16(float lo, float hi) { const f32x2_t v = {lo, hi}; const bf16x2_t b = __builtin_convertvector(v, bf16x2_t); return __builtin_bit_cast(unsigned, b); }
; __device__ __forceinline__ void tconv_list(const float* wg, const float* wu, const float* wd, const float* win, const float* wout, unsigned char* ws, const int ntiles, LAS float* t, const int wv) {
;     ...
; #pragma unroll
;         for (int e = 0; e < 8; ++e) { const int idx = e * 512 + tid, r = idx >> 6, c = idx & 63; t[r * 65 + c] = cur[e]; }
;         __syncthreads();
; #pragma unroll
;         for (int e = 0; e < 4; ++e) { const int idx = e * 512 + tid, n = idx >> 5, kp = idx & 31;
;             const unsigned w = pg8::cvt_pk_bf16(t[(2 * kp) * 65 + n], t[(2 * kp + 1) * 65 + n]);
;             *(unsigned*)(d.Bt + (size_t)(d.brow0 + n) * d.K + d.k0 + 2 * kp) = w; }
;         __syncthreads();
; #pragma unroll
;         for (int e = 0; e < 8; ++e) cur[e] = nxt[e];
;     }
.Ltc2_havea:
	ds_write_b32 v5, v8 offset:0
	ds_write_b32 v5, v9 offset:2080
	ds_write_b32 v5, v10 offset:4160
	ds_write_b32 v5, v11 offset:6240
	ds_write_b32 v5, v12 offset:8320
	ds_write_b32 v5, v13 offset:10400
	ds_write_b32 v5, v14 offset:12480
	ds_write_b32 v5, v15 offset:14560
	v_mad_u32_u24 v4, v2, s30, v3
	s_waitcnt lgkmcnt(0)
	s_barrier
	ds_read2_b32 v[24:25], v6 offset0:0 offset1:65
	ds_read2_b32 v[26:27], v6 offset0:16 offset1:81
	ds_read2_b32 v[28:29], v6 offset0:32 offset1:97
	ds_read2_b32 v[30:31], v6 offset0:48 offset1:113
	s_waitcnt lgkmcnt(3)
	v_cvt_pk_bf16_f32 v32, v24, v25
	s_waitcnt lgkmcnt(2)
	v_cvt_pk_bf16_f32 v33, v26, v27
	s_waitcnt lgkmcnt(1)
	v_cvt_pk_bf16_f32 v34, v28, v29
	s_waitcnt lgkmcnt(0)
	v_cvt_pk_bf16_f32 v35, v30, v31
	global_store_dword v4, v32, s[8:9]
	s_add_u32 s8, s8, s17
	s_addc_u32 s9, s9, 0
	global_store_dword v4, v33, s[8:9]
	s_add_u32 s8, s8, s17
	s_addc_u32 s9, s9, 0
	global_store_dword v4, v34, s[8:9]
	s_add_u32 s8, s8, s17
	s_addc_u32 s9, s9, 0
	global_store_dword v4, v35, s[8:9]
	s_barrier
	s_cmp_eq_u32 s31, 0
	s_cbranch_scc1 .Ltc2_done
	s_mov_b32 s17, s15
	s_mov_b32 s30, s16
	s_mov_b64 s[8:9], s[12:13]
	s_add_u32 s4, s4, 128
	s_cmp_lt_u32 s4, 1408
	s_cselect_b32 s31, 1, 0
	s_cbranch_scc0 .Ltc2_nonextb
	v_writelane_b32 v40, s8, 32
	v_writelane_b32 v40, s9, 33
	s_cmp_lt_u32 s4, 704
	s_cbranch_scc0 .Ltc2_seg1_2
	s_mov_b32 s7, s4
	s_and_b32 s8, s7, 15
	s_lshr_b32 s9, s7, 4
	s_mul_i32 s7, s8, 720896
	s_lshl_b32 s29, s9, 8
	s_add_u32 s7, s7, s29
	s_mul_i32 s29, s28, 11264
	s_add_u32 s7, s7, s29
	s_add_u32 s10, s18, s7
	s_addc_u32 s11, s19, 0
	s_lshr_b32 s7, s9, 1
	s_lshl_b32 s7, s7, 8
	s_and_b32 s29, s9, 1
	s_lshl_b32 s29, s29, 6
	s_add_u32 s7, s7, s29
	s_mul_i32 s7, s7, 2048
	s_lshl_b32 s29, s8, 7
	s_add_u32 s7, s7, s29
	s_mul_i32 s29, s28, 4096
	s_add_u32 s7, s7, s29
	s_add_u32 s12, s26, 0x2100000
	s_addc_u32 s13, s27, 0
	s_add_u32 s12, s12, s7
	s_addc_u32 s13, s13, 0
	s_mov_b32 s14, 90112
	s_mov_b32 s15, 32768
	s_movk_i32 s16, 2048
	s_branch .Ltc2_segend_2

; __device__ __forceinline__ int fresh_tid(int wv) { int l; asm volatile("v_mbcnt_lo_u32_b32 %0, -1, 0\n\tv_mbcnt_hi_u32_b32 %0, -1, %0" : "=v"(l)); return wv * 64 + l; }
; #define LAS __attribute__((address_space(3)))
; __device__ __forceinline__ void tconv_list(const float* wg, const float* wu, const float* wd, const float* win, const float* wout, unsigned char* ws, const int ntiles, LAS float* t, const int wv) {
;     const int tid = fresh_tid(wv); const int G = gridDim.x;
;     float cur[8], nxt[8];
;     int i = blockIdx.x;
;     if (i < ntiles) { const TDesc d = tconv_desc(wg, wu, wd, win, wout, ws, i);
; #pragma unroll
;         for (int e = 0; e < 8; ++e) { const int idx = e * 512 + tid, r = idx >> 6, c = idx & 63; cur[e] = __builtin_nontemporal_load(d.W + (size_t)(d.k0 + r) * d.N + d.n0 + c); } }
.LBB0_1013:
	s_cmp_lt_u32 s2, 172
	s_cbranch_scc1 .Ltc8_skip
	v_writelane_b32 v40, s4, 4
	v_writelane_b32 v40, s5, 5
	v_writelane_b32 v40, s6, 6
	v_writelane_b32 v40, s7, 7
	v_writelane_b32 v40, s8, 8
	v_writelane_b32 v40, s9, 9
	v_writelane_b32 v40, s10, 10
	v_writelane_b32 v40, s11, 11
	v_writelane_b32 v40, s12, 12
	v_writelane_b32 v40, s13, 13
	v_writelane_b32 v40, s14, 14
	v_writelane_b32 v40, s15, 15
	v_writelane_b32 v40, s16, 16
	v_writelane_b32 v40, s17, 17
	v_writelane_b32 v40, s18, 18
	v_writelane_b32 v40, s19, 19
	v_writelane_b32 v40, s20, 20
	v_writelane_b32 v40, s21, 21
	v_writelane_b32 v40, s22, 22
	v_writelane_b32 v40, s23, 23
	v_writelane_b32 v40, s24, 24
	v_writelane_b32 v40, s25, 25
	v_writelane_b32 v40, s26, 26
	v_writelane_b32 v40, s27, 27
	v_writelane_b32 v40, s28, 28
	v_writelane_b32 v40, s29, 29
	v_writelane_b32 v40, s30, 30
	v_writelane_b32 v40, s31, 31
	s_load_dwordx2 s[24:25], s[38:39], 0xd8
	s_load_dwordx2 s[26:27], s[38:39], 0xd0
	s_load_dwordx2 s[18:19], s[38:39], 0xb8
	s_load_dwordx2 s[20:21], s[38:39], 0xc0
	s_load_dwordx2 s[22:23], s[38:39], 0xc8
	v_mbcnt_lo_u32_b32 v0, -1, 0
	v_mbcnt_hi_u32_b32 v0, -1, v0
	s_lshr_b32 s28, s33, 6
	v_lshlrev_b32_e32 v1, 2, v0
	v_lshrrev_b32_e32 v2, 5, v0
	v_and_b32_e32 v3, 31, v0
	s_mul_i32 s7, s28, 260
	v_add_u32_e32 v5, s7, v1
	v_mul_u32_u24_e32 v6, 0x208, v3
	s_lshl_b32 s7, s28, 3
	v_lshl_add_u32 v6, v2, 2, v6
	v_add_u32_e32 v6, s7, v6
	v_lshlrev_b32_e32 v3, 2, v3
	s_sub_u32 s4, s2, 172
	s_add_u32 s4, s4, 1408
	s_waitcnt lgkmcnt(0)
	s_cmp_lt_u32 s4, 704
	s_cbranch_scc0 .Ltc8_seg1_0
	s_mov_b32 s7, s4
	s_and_b32 s8, s7, 15
	s_lshr_b32 s9, s7, 4
	s_mul_i32 s7, s8, 720896
	s_lshl_b32 s29, s9, 8
	s_add_u32 s7, s7, s29
	s_mul_i32 s29, s28, 11264
	s_add_u32 s7, s7, s29
	s_add_u32 s10, s18, s7
	s_addc_u32 s11, s19, 0
	s_lshr_b32 s7, s9, 1
	s_lshl_b32 s7, s7, 8
	s_and_b32 s29, s9, 1
	s_lshl_b32 s29, s29, 6
	s_add_u32 s7, s7, s29
	s_mul_i32 s7, s7, 2048
	s_lshl_b32 s29, s8, 7
	s_add_u32 s7, s7, s29
	s_mul_i32 s29, s28, 4096
	s_add_u32 s7, s7, s29
	s_add_u32 s12, s26, 0x2100000
	s_addc_u32 s13, s27, 0
	s_add_u32 s12, s12, s7
	s_addc_u32 s13, s13, 0
	s_mov_b32 s14, 90112
	s_mov_b32 s15, 32768
	s_movk_i32 s16, 2048
	s_branch .Ltc8_segend_0

; __device__ __forceinline__ void tconv_list(const float* wg, const float* wu, const float* wd, const float* win, const float* wout, unsigned char* ws, const int ntiles, LAS float* t, const int wv) {
;     ...
;     for (; i < ntiles; i += G) {
;         const TDesc d = tconv_desc(wg, wu, wd, win, wout, ws, i);
;         { const TDesc dn = tconv_desc(wg, wu, wd, win, wout, ws, i + G < ntiles ? i + G : i);
; #pragma unroll
;             for (int e = 0; e < 8; ++e) { const int idx = e * 512 + tid, r = idx >> 6, c = idx & 63; nxt[e] = __builtin_nontemporal_load(dn.W + (size_t)(dn.k0 + r) * dn.N + dn.n0 + c); } }
.Ltc8_loop:
	s_add_u32 s4, s4, 84
	s_cmp_lt_u32 s4, 2112
	s_cselect_b32 s31, 1, 0
	s_cbranch_scc0 .Ltc8_nonexta
	v_writelane_b32 v40, s8, 32
	v_writelane_b32 v40, s9, 33
	s_cmp_lt_u32 s4, 704
	s_cbranch_scc0 .Ltc8_seg1_1
	s_mov_b32 s7, s4
	s_and_b32 s8, s7, 15
	s_lshr_b32 s9, s7, 4
	s_mul_i32 s7, s8, 720896
	s_lshl_b32 s29, s9, 8
	s_add_u32 s7, s7, s29
	s_mul_i32 s29, s28, 11264
	s_add_u32 s7, s7, s29
	s_add_u32 s10, s18, s7
	s_addc_u32 s11, s19, 0
	s_lshr_b32 s7, s9, 1
	s_lshl_b32 s7, s7, 8
	s_and_b32 s29, s9, 1
	s_lshl_b32 s29, s29, 6
	s_add_u32 s7, s7, s29
	s_mul_i32 s7, s7, 2048
	s_lshl_b32 s29, s8, 7
	s_add_u32 s7, s7, s29
	s_mul_i32 s29, s28, 4096
	s_add_u32 s7, s7, s29
	s_add_u32 s12, s26, 0x2100000
	s_addc_u32 s13, s27, 0
	s_add_u32 s12, s12, s7
	s_addc_u32 s13, s13, 0
	s_mov_b32 s14, 90112
	s_mov_b32 s15, 32768
	s_movk_i32 s16, 2048
	s_branch .Ltc8_segend_1

; __device__ __forceinline__ unsigned cvt_pk_bf16(float lo, float hi) { const f32x2_t v = {lo, hi}; const bf16x2_t b = __builtin_convertvector(v, bf16x2_t); return __builtin_bit_cast(unsigned, b); }
; __device__ __forceinline__ void tconv_list(const float* wg, const float* wu, const float* wd, const float* win, const float* wout, unsigned char* ws, const int ntiles, LAS float* t, const int wv) {
;     ...
; #pragma unroll
;         for (int e = 0; e < 8; ++e) { const int idx = e * 512 + tid, r = idx >> 6, c = idx & 63; t[r * 65 + c] = cur[e]; }
;         __syncthreads();
; #pragma unroll
;         for (int e = 0; e < 4; ++e) { const int idx = e * 512 + tid, n = idx >> 5, kp = idx & 31;
;             const unsigned w = pg8::cvt_pk_bf16(t[(2 * kp) * 65 + n], t[(2 * kp + 1) * 65 + n]);
;             *(unsigned*)(d.Bt + (size_t)(d.brow0 + n) * d.K + d.k0 + 2 * kp) = w; }
;         __syncthreads();
; #pragma unroll
;         for (int e = 0; e < 8; ++e) cur[e] = nxt[e];
;     }
.Ltc8_havea:
	ds_write_b32 v5, v8 offset:0
	ds_write_b32 v5, v9 offset:2080
	ds_write_b32 v5, v10 offset:4160
	ds_write_b32 v5, v11 offset:6240
	ds_write_b32 v5, v12 offset:8320
	ds_write_b32 v5, v13 offset:10400
	ds_write_b32 v5, v14 offset:12480
	ds_write_b32 v5, v15 offset:14560
	v_mad_u32_u24 v4, v2, s30, v3
	s_waitcnt lgkmcnt(0)
	s_barrier
	ds_read2_b32 v[24:25], v6 offset0:0 offset1:65
	ds_read2_b32 v[26:27], v6 offset0:16 offset1:81
	ds_read2_b32 v[28:29], v6 offset0:32 offset1:97
	ds_read2_b32 v[30:31], v6 offset0:48 offset1:113
	s_waitcnt lgkmcnt(3)
	v_cvt_pk_bf16_f32 v32, v24, v25
	s_waitcnt lgkmcnt(2)
	v_cvt_pk_bf16_f32 v33, v26, v27
	s_waitcnt lgkmcnt(1)
	v_cvt_pk_bf16_f32 v34, v28, v29
	s_waitcnt lgkmcnt(0)
	v_cvt_pk_bf16_f32 v35, v30, v31
	global_store_dword v4, v32, s[8:9]
	s_add_u32 s8, s8, s17
	s_addc_u32 s9, s9, 0
	global_store_dword v4, v33, s[8:9]
	s_add_u32 s8, s8, s17
	s_addc_u32 s9, s9, 0
	global_store_dword v4, v34, s[8:9]
	s_add_u32 s8, s8, s17
	s_addc_u32 s9, s9, 0
	global_store_dword v4, v35, s[8:9]
	s_barrier
	s_cmp_eq_u32 s31, 0
	s_cbranch_scc1 .Ltc8_done
	s_mov_b32 s17, s15
	s_mov_b32 s30, s16
	s_mov_b64 s[8:9], s[12:13]
	s_add_u32 s4, s4, 84
	s_cmp_lt_u32 s4, 2112
	s_cselect_b32 s31, 1, 0
	s_cbranch_scc0 .Ltc8_nonextb
	v_writelane_b32 v40, s8, 32
	v_writelane_b32 v40, s9, 33
	s_cmp_lt_u32 s4, 704
	s_cbranch_scc0 .Ltc8_seg1_2
	s_mov_b32 s7, s4
	s_and_b32 s8, s7, 15
	s_lshr_b32 s9, s7, 4
	s_mul_i32 s7, s8, 720896
	s_lshl_b32 s29, s9, 8
	s_add_u32 s7, s7, s29
	s_mul_i32 s29, s28, 11264
	s_add_u32 s7, s7, s29
	s_add_u32 s10, s18, s7
	s_addc_u32 s11, s19, 0
	s_lshr_b32 s7, s9, 1
	s_lshl_b32 s7, s7, 8
	s_and_b32 s29, s9, 1
	s_lshl_b32 s29, s29, 6
	s_add_u32 s7, s7, s29
	s_mul_i32 s7, s7, 2048
	s_lshl_b32 s29, s8, 7
	s_add_u32 s7, s7, s29
	s_mul_i32 s29, s28, 4096
	s_add_u32 s7, s7, s29
	s_add_u32 s12, s26, 0x2100000
	s_addc_u32 s13, s27, 0
	s_add_u32 s12, s12, s7
	s_addc_u32 s13, s13, 0
	s_mov_b32 s14, 90112
	s_mov_b32 s15, 32768
	s_movk_i32 s16, 2048
	s_branch .Ltc8_segend_2

; __device__ __forceinline__ int fresh_tid(int wv) { int l; asm volatile("v_mbcnt_lo_u32_b32 %0, -1, 0\n\tv_mbcnt_hi_u32_b32 %0, -1, %0" : "=v"(l)); return wv * 64 + l; }
; #define LAS __attribute__((address_space(3)))
; __device__ __forceinline__ unsigned xb_xcc_id() { return (unsigned)__builtin_amdgcn_s_getreg((3 << 11) | 20) & 0xFu; }
; __device__ __forceinline__ void xcd_barrier(unsigned* barw, volatile LAS unsigned* stw, const int wv) {
;     XcdBarrier b; b.bar = barw; b.x = xb_xcc_id(); b.st = stw;
;     asm volatile("s_waitcnt vmcnt(0)" ::: "memory");
;     __syncthreads();
;     if (fresh_tid(wv) == 0) {
;         unsigned* bar = b.bar;
;         __builtin_amdgcn_s_waitcnt(0);
;         unsigned nloc = b.st[0], nx = b.st[1];
;         if (nloc == 0u) { xcd_barrier_complete(bar, b.x, nloc, nx); b.st[0] = nloc; b.st[1] = nx; }
.Ltc8_done:
	v_readlane_b32 s4, v40, 4
	v_readlane_b32 s5, v40, 5
	v_readlane_b32 s6, v40, 6
	v_readlane_b32 s7, v40, 7
	v_readlane_b32 s8, v40, 8
	v_readlane_b32 s9, v40, 9
	v_readlane_b32 s10, v40, 10
	v_readlane_b32 s11, v40, 11
	v_readlane_b32 s12, v40, 12
	v_readlane_b32 s13, v40, 13
	v_readlane_b32 s14, v40, 14
	v_readlane_b32 s15, v40, 15
	v_readlane_b32 s16, v40, 16
	v_readlane_b32 s17, v40, 17
	v_readlane_b32 s18, v40, 18
	v_readlane_b32 s19, v40, 19
	v_readlane_b32 s20, v40, 20
	v_readlane_b32 s21, v40, 21
	v_readlane_b32 s22, v40, 22
	v_readlane_b32 s23, v40, 23
	v_readlane_b32 s24, v40, 24
	v_readlane_b32 s25, v40, 25
	v_readlane_b32 s26, v40, 26
	v_readlane_b32 s27, v40, 27
	v_readlane_b32 s28, v40, 28
	v_readlane_b32 s29, v40, 29
	v_readlane_b32 s30, v40, 30
	v_readlane_b32 s31, v40, 31
	s_nop 4
.Ltc8_skip:
	s_getreg_b32 s4, hwreg(HW_REG_XCC_ID, 0, 4)
	s_waitcnt vmcnt(0)
	s_waitcnt vmcnt(0) lgkmcnt(0)
	s_barrier
	v_mbcnt_lo_u32_b32 v0, -1, 0
	v_mbcnt_hi_u32_b32 v0, -1, v0
	s_nop 0
	v_cmp_eq_u32_e32 vcc, s74, v0
	s_and_saveexec_b64 s[0:1], vcc
	s_cbranch_execz .LBB0_1065
	s_add_u32 s2, s8, 0x200
	s_addc_u32 s3, s9, 0
	s_add_i32 s5, 0, 0x23ff0
	v_mov_b32_e32 v0, s5
	s_waitcnt vmcnt(0) expcnt(0) lgkmcnt(0)
	ds_read_b32 v2, v0
	s_add_i32 s5, 0, 0x23ff4
	v_mov_b32_e32 v0, s5
	ds_read_b32 v0, v0
	s_and_b32 s20, s4, 15
	s_waitcnt lgkmcnt(1)
	v_cmp_ne_u32_e32 vcc, 0, v2
	s_cbranch_vccnz .LBB0_1029
	s_add_u32 s4, s8, 0x1000
	s_addc_u32 s5, s9, 0
	s_add_u32 s6, s8, 0x1100
	s_addc_u32 s7, s9, 0
	s_add_u32 s10, s8, 0x1200
	s_addc_u32 s11, s9, 0
	s_add_u32 s12, s8, 0x1300
	s_addc_u32 s13, s9, 0
	s_mov_b32 s21, 1
	v_mov_b32_e32 v16, 0
	s_branch .LBB0_1017
